# F1 prep hand-written in two copies: common path steps the six next-item row addresses by +-128 KiB and issues each load as soon as its registers are consumed (spread through the VALU work), generic pa
# speedup vs baseline: 1.0065x; 1.0065x over previous
.LBB0_864:
	v_xor_b32_e32 v2, 63, v114
	v_cndmask_b32_e64 v2, v2, v114, s[38:39]
	s_lshl_b32 s12, s17, 5
	s_lshl_b32 s13, s18, 3
	v_add_u32_e32 v4, s21, v2
	s_and_b32 s12, s12, 0x3c0
	s_ashr_i32 s17, s13, 31
	v_ashrrev_i32_e32 v5, 31, v4
	s_add_u32 s12, s12, s13
	v_lshlrev_b64 v[4:5], 10, v[4:5]
	s_addc_u32 s13, 0, s17
	v_lshl_add_u64 v[4:5], s[12:13], 0, v[4:5]
	v_lshlrev_b64 v[4:5], 1, v[4:5]
	v_lshl_add_u64 v[12:13], s[36:37], 0, v[4:5]
	s_mov_b32 s12, 0x16600000
	s_mul_i32 s16, s16, 0x2100000
	v_add_co_u32_e32 v6, vcc, s12, v12
	s_add_u32 s12, s36, s16
	s_addc_u32 s13, s37, 0
	v_addc_co_u32_e32 v7, vcc, 0, v13, vcc
	v_lshl_add_u64 v[20:21], s[12:13], 0, v[4:5]
	s_mov_b32 s12, 0x32380000
	v_add_co_u32_e32 v8, vcc, s12, v20
	s_mov_b32 s12, 0x3a780000
	s_nop 0
	v_addc_co_u32_e32 v9, vcc, 0, v21, vcc
	v_add_co_u32_e32 v14, vcc, s12, v12
	v_mov_b32_e32 v220, v6
	v_mov_b32_e32 v221, v7
	global_load_dwordx4 v[4:7], v[6:7], off
	s_nop 0
	v_mov_b32_e32 v222, v8
	v_mov_b32_e32 v223, v9
	global_load_dwordx4 v[8:11], v[8:9], off
	v_addc_co_u32_e32 v15, vcc, 0, v13, vcc
	v_add_co_u32_e32 v16, vcc, 0x18700000, v12
	s_nop 1
	v_addc_co_u32_e32 v17, vcc, 0, v13, vcc
	v_add_co_u32_e32 v22, vcc, 0x36580000, v20
	v_mov_b32_e32 v224, v14
	v_mov_b32_e32 v225, v15
	global_load_dwordx4 v[12:15], v[14:15], off
	s_nop 0
	v_mov_b32_e32 v226, v16
	v_mov_b32_e32 v227, v17
	global_load_dwordx4 v[16:19], v[16:17], off
	v_addc_co_u32_e32 v23, vcc, 0, v21, vcc
	v_add_co_u32_e32 v24, vcc, 0x29f80000, v20
	s_nop 1
	v_addc_co_u32_e32 v25, vcc, 0, v21, vcc
	v_mov_b32_e32 v228, v22
	v_mov_b32_e32 v229, v23
	global_load_dwordx4 v[20:23], v[22:23], off
	s_nop 0
	v_mov_b32_e32 v230, v24
	v_mov_b32_e32 v231, v25
	global_load_dwordx4 v[24:27], v[24:25], off
.LBB0_865:
	s_andn2_b64 vcc, exec, s[8:9]
	s_cbranch_vccnz .LBB0_911
	v_writelane_b32 v254, s24, 44
	s_ashr_i32 s8, s18, 1
	s_lshl_b32 s12, s18, 3
	v_writelane_b32 v254, s25, 45
	s_and_b32 s20, s18, 3
	s_and_b32 s9, s8, -2
	s_lshl_b32 s17, s18, 5
	s_lshl_b32 s22, s18, 4
	v_writelane_b32 v254, s12, 46
	s_ashr_i32 s12, s12, 31
	v_writelane_b32 v254, s12, 47
	s_add_u32 s12, s36, 0x16600000
	s_addc_u32 s13, s37, 0
	v_writelane_b32 v254, s12, 48
	v_lshrrev_b32_e32 v2, 4, v114
	v_and_b32_e32 v28, 15, v1
	v_writelane_b32 v254, s13, 49
	s_add_u32 s12, s36, 0x32380000
	v_writelane_b32 v254, s12, 50
	s_addc_u32 s12, s37, 0
	v_writelane_b32 v254, s12, 51
	s_add_u32 s12, s36, 0x3a780000
	s_addc_u32 s13, s37, 0
	v_writelane_b32 v254, s12, 52
	v_lshlrev_b32_e32 v32, 2, v2
	v_lshlrev_b32_e32 v34, 3, v2
	v_writelane_b32 v254, s13, 53
	s_add_u32 s12, s36, 0x18700000
	s_addc_u32 s13, s37, 0
	v_writelane_b32 v254, s12, 54
	v_lshl_or_b32 v43, s8, 4, v28
	v_mul_lo_u32 v44, v43, s76
	v_writelane_b32 v254, s13, 55
	s_add_u32 s12, s36, 0x36580000
	v_writelane_b32 v254, s12, 56
	s_addc_u32 s12, s37, 0
	v_writelane_b32 v254, s12, 57
	s_add_u32 s12, s36, 0x29f80000
	v_writelane_b32 v254, s12, 58
	s_addc_u32 s12, s37, 0
	s_cmp_le_i32 s9, s20
	s_cselect_b64 s[28:29], -1, 0
	s_or_b32 s21, s8, 1
	v_writelane_b32 v254, s12, 59
	s_cmp_le_i32 s21, s20
	s_cselect_b64 s[24:25], -1, 0
	s_lshl_b32 s12, s20, 4
	s_lshl_b32 s19, s20, 5
	v_readlane_b32 s26, v254, 32
	v_or_b32_e32 v30, s12, v28
	v_or_b32_e32 v33, s12, v32
	s_add_i32 s12, s26, s19
	v_add_u32_e32 v119, s12, v34
	v_readlane_b32 s12, v254, 33
	v_readlane_b32 s34, v254, 37
	s_add_i32 s23, 0, 0x12000
	v_mov_b32_e32 v35, s12
	v_readlane_b32 s12, v254, 34
	s_waitcnt vmcnt(0)
	v_mad_u32_u24 v120, v30, s76, v35
	v_mul_u32_u24_e32 v31, 0x90, v30
	v_mov_b32_e32 v35, s12
	v_readlane_b32 s12, v254, 35
	v_mad_u32_u24 v122, v30, s76, v35
	v_readlane_b32 s27, v254, 36
	v_mov_b32_e32 v35, s12
	s_add_i32 s12, s34, s19
	v_add_u32_e32 v129, s12, v34
	s_and_b32 s12, s18, 2
	s_cmp_eq_u32 s9, s12
	s_cselect_b64 s[40:41], -1, 0
	s_cmp_lt_i32 s18, 2
	v_add3_u32 v118, s23, v31, v34
	v_add3_u32 v126, s27, v31, v34
	v_bfe_u32 v31, v1, 2, 2
	s_cselect_b64 s[42:43], -1, 0
	s_cmp_eq_u32 s18, 0
	v_mad_u32_u24 v124, v30, s76, v35
	v_or_b32_e32 v35, v34, v31
	s_cselect_b32 s12, 16, 48
	s_cselect_b32 s13, 0, 64
	v_or3_b32 v31, s17, v31, v34
	v_mul_lo_u32 v31, v31, s76
	s_add_i32 s16, s13, 0
	v_or_b32_e32 v39, s12, v28
	s_lshl_b32 s12, s18, 6
	v_add_u32_e32 v31, s16, v31
	s_add_i32 s16, s12, s23
	v_mov_b32_e32 v40, s16
	v_mad_u32_u24 v40, v39, s76, v40
	v_mad_u32_u24 v39, v39, s76, 0
	s_cmp_lt_i32 s18, 4
	v_add_u32_e32 v41, s13, v39
	v_add_u32_e32 v39, s12, v39
	s_cselect_b64 s[12:13], -1, 0
	s_and_b32 s16, s17, 32
	v_add_u32_e32 v44, 0x1200, v44
	v_mad_u32_u24 v35, v35, s76, 0
	v_add_u32_e32 v130, 0, v44
	s_cmp_gt_u32 s20, 1
	v_lshlrev_b32_e32 v36, 3, v1
	v_writelane_b32 v254, s17, 60
	v_add_u32_e32 v42, s16, v35
	v_add_u32_e32 v45, s23, v44
	v_add_u32_e32 v44, s16, v130
	s_cselect_b64 s[16:17], -1, 0
	s_add_i32 s8, s23, s19
	v_mad_u32_u24 v116, v30, s76, 0
	v_and_b32_e32 v36, 24, v36
	v_add_u32_e32 v132, s8, v34
	s_add_i32 s8, s27, s19
	v_and_b32_e32 v117, 48, v1
	v_add_u32_e32 v128, v35, v36
	v_or_b32_e32 v37, s19, v34
	v_add_u32_e32 v38, s19, v116
	v_add_u32_e32 v133, s8, v34
	v_add_u32_e32 v35, s19, v35
	v_readlane_b32 s19, v254, 38
	s_lshl_b32 s8, s20, 6
	v_lshlrev_b32_e32 v1, 1, v1
	s_add_i32 s8, s19, s8
	v_and_b32_e32 v46, 48, v114
	v_and_b32_e32 v1, 0x60, v1
	v_add_u32_e32 v135, s8, v46
	s_and_b32 s8, s18, 0xffffffc
	v_lshl_or_b32 v1, s20, 3, v1
	v_or_b32_e32 v46, s8, v2
	v_add_u32_e32 v136, s26, v1
	v_add_u32_e32 v137, 0, v1
	v_lshrrev_b32_e32 v1, 3, v0
	s_mov_b32 s8, 0xffffff0
	v_and_or_b32 v1, v1, s8, v28
	s_lshl_b32 s8, s9, 4
	s_lshl_b32 s30, s9, 5
	v_bfe_u32 v47, v0, 6, 1
	v_lshlrev_b32_e32 v104, 4, v0
	v_or_b32_e32 v0, s8, v28
	v_or_b32_e32 v48, 2, v33
	v_or_b32_e32 v49, 3, v33
	s_cmp_lg_u32 s9, s20
	v_lshl_add_u32 v134, v30, 2, s19
	v_mul_lo_u32 v140, v0, s76
	v_cmp_lt_i32_e64 s[44:45], v0, v33
	v_cmp_gt_i32_e64 s[46:47], v0, v33
	v_cmp_lt_i32_e64 s[18:19], v0, v48
	v_cmp_lt_i32_e64 s[62:63], v0, v49
	v_or_b32_e32 v0, s8, v32
	s_cselect_b64 s[64:65], -1, 0
	s_lshl_b32 s8, s21, 4
	v_or_b32_e32 v50, 1, v0
	v_cmp_eq_u32_e32 vcc, v0, v30
	v_or_b32_e32 v28, s8, v28
	v_cmp_lt_i32_e64 s[52:53], v50, v30
	v_cndmask_b32_e64 v106, 0, 1.0, vcc
	v_cmp_eq_u32_e32 vcc, v50, v30
	v_or_b32_e32 v50, 3, v0
	v_cmp_lt_i32_e64 s[70:71], v28, v48
	v_cndmask_b32_e64 v107, 0, 1.0, vcc
	v_or_b32_e32 v51, 2, v0
	v_cmp_eq_u32_e32 vcc, v50, v30
	v_writelane_b32 v254, s70, 61
	v_cmp_lt_i32_e64 s[66:67], v28, v33
	v_cndmask_b32_e64 v109, 0, 1.0, vcc
	v_cmp_eq_u32_e32 vcc, v51, v30
	v_cmp_gt_i32_e64 s[68:69], v28, v33
	v_writelane_b32 v254, s71, 62
	v_cmp_lt_i32_e64 s[70:71], v28, v49
	v_mul_lo_u32 v141, v28, s76
	v_or_b32_e32 v28, s8, v32
	v_cndmask_b32_e64 v108, 0, 1.0, vcc
	v_or_b32_e32 v32, 1, v28
	v_cmp_eq_u32_e32 vcc, v28, v30
	v_or_b32_e32 v43, 16, v43
	v_cmp_lt_i32_e64 s[74:75], v32, v30
	v_cndmask_b32_e64 v110, 0, 1.0, vcc
	v_cmp_eq_u32_e32 vcc, v32, v30
	v_or_b32_e32 v32, 3, v28
	v_lshlrev_b32_e32 v2, 5, v2
	v_mul_lo_u32 v1, v1, s76
	v_mul_lo_u32 v43, v43, s76
	v_writelane_b32 v254, s70, 63
	s_lshl_b32 s31, s21, 5
	v_cndmask_b32_e64 v111, 0, 1.0, vcc
	v_or_b32_e32 v33, 2, v28
	v_cmp_eq_u32_e32 vcc, v32, v30
	v_mad_u32_u24 v29, v114, s76, 0
	v_mad_u32_u24 v37, v30, s76, v37
	v_lshlrev_b32_e32 v46, 4, v46
	v_lshl_or_b32 v138, v47, 4, v2
	v_add_u32_e32 v139, 0, v1
	v_lshl_or_b32 v2, v47, 6, v117
	v_add_u32_e32 v1, s26, v1
	v_add_u32_e32 v47, 0, v140
	v_add_u32_e32 v43, 0, v43
	v_cmp_lt_i32_e64 s[48:49], v0, v30
	v_cmp_gt_i32_e64 s[50:51], v0, v30
	v_cmp_lt_i32_e64 s[54:55], v51, v30
	v_cmp_gt_i32_e64 s[56:57], v51, v30
	v_cmp_lt_i32_e64 s[58:59], v50, v30
	v_cmp_gt_i32_e64 s[60:61], v50, v30
	v_writelane_b32 v255, s71, 0
	v_cmp_lt_i32_e64 s[70:71], v28, v30
	v_cmp_gt_i32_e64 s[72:73], v28, v30
	v_cndmask_b32_e64 v113, 0, 1.0, vcc
	v_cmp_eq_u32_e32 vcc, v33, v30
	v_cmp_lt_i32_e64 s[76:77], v33, v30
	s_cmp_lg_u32 s21, s20
	v_cmp_gt_i32_e64 s[78:79], v33, v30
	v_add_u32_e32 v33, s23, v140
	v_add_u32_e32 v48, s23, v141
	v_add_u32_e32 v49, s34, v140
	v_add_u32_e32 v50, s34, v141
	v_add_u32_e32 v51, s27, v140
	v_lshlrev_b32_e32 v0, 1, v0
	v_add_u32_e32 v52, s27, v141
	v_lshlrev_b32_e32 v28, 1, v28
	v_cmp_ne_u32_e64 s[38:39], 63, v114
	v_xor_b32_e32 v115, 63, v114
	v_add_u32_e32 v121, v120, v34
	v_add_u32_e32 v123, v122, v34
	v_add_u32_e32 v125, v124, v34
	v_add_u32_e32 v127, v116, v34
	v_add_u32_e32 v131, s34, v117
	v_ashrrev_i32_e32 v105, 31, v104
	v_cndmask_b32_e64 v112, 0, 1.0, vcc
	s_cselect_b64 s[20:21], -1, 0
	v_add_u32_e32 v142, s22, v29
	s_lshl_b32 s26, s90, 6
	v_add_u32_e32 v143, v47, v117
	v_add_u32_e32 v144, v43, v117
	v_add_u32_e32 v145, 0, v37
	v_add_u32_e32 v146, v38, v34
	v_add_u32_e32 v147, v31, v36
	v_add_u32_e32 v148, v40, v117
	v_add_u32_e32 v149, v41, v34
	v_add_u32_e32 v150, v39, v117
	v_add_u32_e32 v151, v45, v117
	v_add_u32_e32 v152, v49, v117
	v_add_u32_e32 v153, v50, v117
	v_add_u32_e32 v154, v35, v36
	v_add_u32_e32 v155, v51, v117
	v_add_u32_e32 v156, v33, v117
	v_add_u32_e32 v157, v116, v0
	v_add_u32_e32 v158, v52, v117
	v_add_u32_e32 v159, v48, v117
	v_add_u32_e32 v160, v116, v28
	v_add_u32_e32 v161, v139, v2
	v_add_u32_e32 v162, v1, v138
	v_add_u32_e32 v163, v42, v36
	v_add_u32_e32 v164, v44, v34
	v_add_u32_e32 v165, v116, v46
	s_sub_i32 s27, 0x82, s90
	v_cmp_lt_i32_e64 s[80:81], v32, v30
	v_cmp_gt_i32_e64 s[82:83], v32, v30
	v_add_u32_e32 v166, v116, v117
	v_add_u32_e32 v167, s30, v118
	v_add_u32_e32 v168, v119, v140
	v_add_u32_e32 v169, s30, v121
	v_add_u32_e32 v170, s30, v123
	v_add_u32_e32 v171, s30, v126
	v_add_u32_e32 v172, s30, v125
	v_add_u32_e32 v173, s30, v127
	v_add_u32_e32 v174, s31, v118
	v_add_u32_e32 v175, v119, v141
	v_add_u32_e32 v176, s31, v121
	v_add_u32_e32 v177, s31, v123
	v_add_u32_e32 v178, s31, v126
	v_add_u32_e32 v179, s31, v125
	v_add_u32_e32 v182, s31, v127
	v_add_u32_e32 v183, v120, v117
	v_add_u32_e32 v184, s30, v128
	v_add_u32_e32 v185, s31, v128
	v_add_u32_e32 v186, v129, v140
	v_add_u32_e32 v187, v129, v141
	v_add_u32_e32 v188, 0x14400, v145
	v_add_u32_e32 v189, 0x16800, v145
	v_add_u32_e32 v190, v130, v117
	v_add_u32_e32 v191, v131, v140
	v_add_u32_e32 v192, v131, v141
	v_add_u32_e32 v193, v132, v140
	v_add_u32_e32 v194, v133, v140
	v_add_u32_e32 v195, v132, v141
	v_add_u32_e32 v196, v133, v141
	v_add_u32_e32 v197, v124, v117
	v_add_u32_e32 v200, v122, v117
	v_add_u32_e32 v201, v137, v140
	v_add_u32_e32 v204, v136, v141
	v_add_u32_e32 v205, 8, v165
	v_add_u32_e32 v206, v137, v141
	v_add_u32_e32 v207, v139, v138
	v_mov_b32_e32 v212, 1.0
	v_mov_b32_e32 v213, 1.0
	v_mov_b32_e32 v214, 1.0
	v_mov_b32_e32 v215, 1.0
	v_mov_b32_e32 v216, 1.0
	v_mov_b32_e32 v217, 1.0
	v_mov_b32_e32 v218, 1.0
	v_mov_b32_e32 v219, 1.0
	v_readlane_b32 s98, v253, 7
	v_readlane_b32 s99, v253, 0
	s_nop 3
	s_cmp_eq_u32 s98, 0x100
	s_cselect_b32 s98, 1, 0
	s_lshr_b32 s30, s99, 2
	s_mul_i32 s31, s30, 0x84
	s_add_i32 s99, s31, 4
	s_mov_b32 s31, 0x20000
	s_bitcmp1_b32 s30, 0
	s_cselect_b32 s30, 0xfffe0000, s31
	s_cselect_b32 s31, -1, 0
.LBB0_867:
	s_waitcnt vmcnt(4)
	s_add_i32 s91, s90, 1
	s_cmp_ge_i32 s91, s88
	s_cselect_b64 s[22:23], -1, 0
	s_cmp_lg_u32 s91, s99
	s_cselect_b32 s8, s98, 0
	s_andn2_b32 s8, s8, s22
	s_cmp_lg_u32 s8, 0
	s_cbranch_scc0 .Lf1_prep_slow
	v_cvt_f32_f16 v28, v24
	v_lshrrev_b32_e32 v0, 16, v24
	v_cvt_f32_f16 v29, v0
	v_cvt_f32_f16 v30, v25
	v_lshrrev_b32_e32 v0, 16, v25
	v_cvt_f32_f16 v31, v0
	v_cvt_f32_f16 v32, v26
	v_lshrrev_b32_e32 v0, 16, v26
	v_cvt_f32_f16 v33, v0
	v_cvt_f32_f16 v34, v27
	v_lshrrev_b32_e32 v0, 16, v27
	v_cvt_f32_f16 v35, v0
	v_mul_f32_e32 v28, 0x3fb8aa3b, v28
	v_mul_f32_e32 v29, 0x3fb8aa3b, v29
	v_mul_f32_e32 v30, 0x3fb8aa3b, v30
	v_mul_f32_e32 v31, 0x3fb8aa3b, v31
	v_mul_f32_e32 v32, 0x3fb8aa3b, v32
	v_mul_f32_e32 v33, 0x3fb8aa3b, v33
	v_mul_f32_e32 v34, 0x3fb8aa3b, v34
	v_mul_f32_e32 v35, 0x3fb8aa3b, v35
	v_lshl_add_u64 v[230:231], v[230:231], 0, s[30:31]
	global_load_dwordx4 v[24:27], v[230:231], off
	v_add_f32_dpp v28, v28, v28 row_shr:1 row_mask:0xf bank_mask:0xf bound_ctrl:1
	v_add_f32_dpp v29, v29, v29 row_shr:1 row_mask:0xf bank_mask:0xf bound_ctrl:1
	v_add_f32_dpp v30, v30, v30 row_shr:1 row_mask:0xf bank_mask:0xf bound_ctrl:1
	v_add_f32_dpp v31, v31, v31 row_shr:1 row_mask:0xf bank_mask:0xf bound_ctrl:1
	v_add_f32_dpp v32, v32, v32 row_shr:1 row_mask:0xf bank_mask:0xf bound_ctrl:1
	v_add_f32_dpp v33, v33, v33 row_shr:1 row_mask:0xf bank_mask:0xf bound_ctrl:1
	v_add_f32_dpp v34, v34, v34 row_shr:1 row_mask:0xf bank_mask:0xf bound_ctrl:1
	v_add_f32_dpp v35, v35, v35 row_shr:1 row_mask:0xf bank_mask:0xf bound_ctrl:1
	v_add_f32_dpp v28, v28, v28 row_shr:2 row_mask:0xf bank_mask:0xf bound_ctrl:1
	v_add_f32_dpp v29, v29, v29 row_shr:2 row_mask:0xf bank_mask:0xf bound_ctrl:1
	v_add_f32_dpp v30, v30, v30 row_shr:2 row_mask:0xf bank_mask:0xf bound_ctrl:1
	v_add_f32_dpp v31, v31, v31 row_shr:2 row_mask:0xf bank_mask:0xf bound_ctrl:1
	v_add_f32_dpp v32, v32, v32 row_shr:2 row_mask:0xf bank_mask:0xf bound_ctrl:1
	v_add_f32_dpp v33, v33, v33 row_shr:2 row_mask:0xf bank_mask:0xf bound_ctrl:1
	v_add_f32_dpp v34, v34, v34 row_shr:2 row_mask:0xf bank_mask:0xf bound_ctrl:1
	v_add_f32_dpp v35, v35, v35 row_shr:2 row_mask:0xf bank_mask:0xf bound_ctrl:1
	v_add_f32_dpp v28, v28, v28 row_shr:4 row_mask:0xf bank_mask:0xf bound_ctrl:1
	v_add_f32_dpp v29, v29, v29 row_shr:4 row_mask:0xf bank_mask:0xf bound_ctrl:1
	v_add_f32_dpp v30, v30, v30 row_shr:4 row_mask:0xf bank_mask:0xf bound_ctrl:1
	v_add_f32_dpp v31, v31, v31 row_shr:4 row_mask:0xf bank_mask:0xf bound_ctrl:1
	v_add_f32_dpp v32, v32, v32 row_shr:4 row_mask:0xf bank_mask:0xf bound_ctrl:1
	v_add_f32_dpp v33, v33, v33 row_shr:4 row_mask:0xf bank_mask:0xf bound_ctrl:1
	v_add_f32_dpp v34, v34, v34 row_shr:4 row_mask:0xf bank_mask:0xf bound_ctrl:1
	v_add_f32_dpp v35, v35, v35 row_shr:4 row_mask:0xf bank_mask:0xf bound_ctrl:1
	v_add_f32_dpp v28, v28, v28 row_shr:8 row_mask:0xf bank_mask:0xf bound_ctrl:1
	v_add_f32_dpp v29, v29, v29 row_shr:8 row_mask:0xf bank_mask:0xf bound_ctrl:1
	v_add_f32_dpp v30, v30, v30 row_shr:8 row_mask:0xf bank_mask:0xf bound_ctrl:1
	v_add_f32_dpp v31, v31, v31 row_shr:8 row_mask:0xf bank_mask:0xf bound_ctrl:1
	v_add_f32_dpp v32, v32, v32 row_shr:8 row_mask:0xf bank_mask:0xf bound_ctrl:1
	v_add_f32_dpp v33, v33, v33 row_shr:8 row_mask:0xf bank_mask:0xf bound_ctrl:1
	v_add_f32_dpp v34, v34, v34 row_shr:8 row_mask:0xf bank_mask:0xf bound_ctrl:1
	v_add_f32_dpp v35, v35, v35 row_shr:8 row_mask:0xf bank_mask:0xf bound_ctrl:1
	v_add_f32_dpp v28, v28, v28 row_bcast:15 row_mask:0xa bank_mask:0xf
	v_add_f32_dpp v29, v29, v29 row_bcast:15 row_mask:0xa bank_mask:0xf
	v_add_f32_dpp v30, v30, v30 row_bcast:15 row_mask:0xa bank_mask:0xf
	v_add_f32_dpp v31, v31, v31 row_bcast:15 row_mask:0xa bank_mask:0xf
	v_add_f32_dpp v32, v32, v32 row_bcast:15 row_mask:0xa bank_mask:0xf
	v_add_f32_dpp v33, v33, v33 row_bcast:15 row_mask:0xa bank_mask:0xf
	v_add_f32_dpp v34, v34, v34 row_bcast:15 row_mask:0xa bank_mask:0xf
	v_add_f32_dpp v35, v35, v35 row_bcast:15 row_mask:0xa bank_mask:0xf
	v_add_f32_dpp v28, v28, v28 row_bcast:31 row_mask:0xc bank_mask:0xf
	v_add_f32_dpp v29, v29, v29 row_bcast:31 row_mask:0xc bank_mask:0xf
	v_add_f32_dpp v30, v30, v30 row_bcast:31 row_mask:0xc bank_mask:0xf
	v_add_f32_dpp v31, v31, v31 row_bcast:31 row_mask:0xc bank_mask:0xf
	v_add_f32_dpp v32, v32, v32 row_bcast:31 row_mask:0xc bank_mask:0xf
	v_add_f32_dpp v33, v33, v33 row_bcast:31 row_mask:0xc bank_mask:0xf
	v_add_f32_dpp v34, v34, v34 row_bcast:31 row_mask:0xc bank_mask:0xf
	v_add_f32_dpp v35, v35, v35 row_bcast:31 row_mask:0xc bank_mask:0xf
	v_exp_f32_e32 v36, v28
	v_lshlrev_b32_e32 v68, 16, v16
	v_and_b32_e32 v69, 0xffff0000, v16
	v_exp_f32_e32 v37, v29
	v_lshlrev_b32_e32 v70, 16, v17
	v_and_b32_e32 v71, 0xffff0000, v17
	v_exp_f32_e32 v38, v30
	v_lshlrev_b32_e32 v72, 16, v18
	v_and_b32_e32 v73, 0xffff0000, v18
	v_exp_f32_e32 v39, v31
	v_lshlrev_b32_e32 v74, 16, v19
	v_and_b32_e32 v75, 0xffff0000, v19
	v_lshl_add_u64 v[226:227], v[226:227], 0, s[30:31]
	global_load_dwordx4 v[16:19], v[226:227], off
	v_exp_f32_e32 v40, v32
	v_lshlrev_b32_e32 v76, 16, v4
	v_and_b32_e32 v77, 0xffff0000, v4
	v_exp_f32_e32 v41, v33
	v_lshlrev_b32_e32 v78, 16, v5
	v_and_b32_e32 v79, 0xffff0000, v5
	v_exp_f32_e32 v42, v34
	v_lshlrev_b32_e32 v80, 16, v6
	v_and_b32_e32 v81, 0xffff0000, v6
	v_exp_f32_e32 v43, v35
	v_lshlrev_b32_e32 v82, 16, v7
	v_and_b32_e32 v83, 0xffff0000, v7
	v_lshl_add_u64 v[220:221], v[220:221], 0, s[30:31]
	global_load_dwordx4 v[4:7], v[220:221], off
	v_exp_f32_e64 v44, -v28
	v_lshlrev_b32_e32 v84, 16, v20
	v_and_b32_e32 v85, 0xffff0000, v20
	v_exp_f32_e64 v45, -v29
	v_lshlrev_b32_e32 v86, 16, v21
	v_and_b32_e32 v87, 0xffff0000, v21
	v_exp_f32_e64 v46, -v30
	v_lshlrev_b32_e32 v88, 16, v22
	v_and_b32_e32 v89, 0xffff0000, v22
	v_exp_f32_e64 v47, -v31
	v_lshlrev_b32_e32 v90, 16, v23
	v_and_b32_e32 v91, 0xffff0000, v23
	v_lshl_add_u64 v[228:229], v[228:229], 0, s[30:31]
	global_load_dwordx4 v[20:23], v[228:229], off
	v_exp_f32_e64 v48, -v32
	v_lshlrev_b32_e32 v92, 16, v8
	v_and_b32_e32 v93, 0xffff0000, v8
	v_exp_f32_e64 v49, -v33
	v_lshlrev_b32_e32 v94, 16, v9
	v_and_b32_e32 v95, 0xffff0000, v9
	v_exp_f32_e64 v50, -v34
	v_lshlrev_b32_e32 v96, 16, v10
	v_and_b32_e32 v97, 0xffff0000, v10
	v_exp_f32_e64 v51, -v35
	v_lshlrev_b32_e32 v98, 16, v11
	v_and_b32_e32 v99, 0xffff0000, v11
	v_lshl_add_u64 v[222:223], v[222:223], 0, s[30:31]
	global_load_dwordx4 v[8:11], v[222:223], off
	v_mov_b32_dpp v212, v36 wave_shr:1 row_mask:0xf bank_mask:0xf
	v_mov_b32_dpp v213, v37 wave_shr:1 row_mask:0xf bank_mask:0xf
	v_mov_b32_dpp v214, v38 wave_shr:1 row_mask:0xf bank_mask:0xf
	v_mov_b32_dpp v215, v39 wave_shr:1 row_mask:0xf bank_mask:0xf
	v_mov_b32_dpp v216, v40 wave_shr:1 row_mask:0xf bank_mask:0xf
	v_mov_b32_dpp v217, v41 wave_shr:1 row_mask:0xf bank_mask:0xf
	v_mov_b32_dpp v218, v42 wave_shr:1 row_mask:0xf bank_mask:0xf
	v_mov_b32_dpp v219, v43 wave_shr:1 row_mask:0xf bank_mask:0xf
	v_readlane_b32 s9, v254, 60
	s_add_i32 s9, s9, 0x21c00
	v_mov_b32_e32 v0, s9
	s_mov_b64 s[84:85], exec
	s_andn2_b64 exec, exec, s[38:39]
	ds_write_b128 v0, v[36:39]
	ds_write_b128 v0, v[40:43] offset:16
	s_mov_b64 exec, s[84:85]
	v_pk_mul_f32 v[68:69], v[212:213], v[68:69] neg_lo:[0,1] neg_hi:[0,1]
	v_pk_mul_f32 v[70:71], v[214:215], v[70:71] neg_lo:[0,1] neg_hi:[0,1]
	v_pk_mul_f32 v[72:73], v[216:217], v[72:73] neg_lo:[0,1] neg_hi:[0,1]
	v_pk_mul_f32 v[74:75], v[218:219], v[74:75] neg_lo:[0,1] neg_hi:[0,1]
	v_pk_mul_f32 v[76:77], v[36:37], v[76:77]
	v_pk_mul_f32 v[78:79], v[38:39], v[78:79]
	v_pk_mul_f32 v[80:81], v[40:41], v[80:81]
	v_pk_mul_f32 v[82:83], v[42:43], v[82:83]
	v_pk_mul_f32 v[84:85], v[44:45], v[84:85]
	v_pk_mul_f32 v[86:87], v[46:47], v[86:87]
	v_pk_mul_f32 v[88:89], v[48:49], v[88:89]
	v_pk_mul_f32 v[90:91], v[50:51], v[90:91]
	v_pk_mul_f32 v[92:93], v[44:45], v[92:93]
	v_pk_mul_f32 v[94:95], v[46:47], v[94:95]
	v_pk_mul_f32 v[96:97], v[48:49], v[96:97]
	v_pk_mul_f32 v[98:99], v[50:51], v[98:99]
	v_cvt_pk_bf16_f32 v52, v68, v69
	v_cvt_pk_bf16_f32 v53, v70, v71
	v_cvt_pk_bf16_f32 v54, v72, v73
	v_cvt_pk_bf16_f32 v55, v74, v75
	v_cvt_pk_bf16_f32 v56, v76, v77
	v_cvt_pk_bf16_f32 v57, v78, v79
	v_cvt_pk_bf16_f32 v58, v80, v81
	v_cvt_pk_bf16_f32 v59, v82, v83
	ds_write_b128 v142, v[52:55]
	ds_write_b128 v142, v[56:59] offset:27648
	v_cvt_pk_bf16_f32 v60, v84, v85
	v_cvt_pk_bf16_f32 v61, v86, v87
	v_cvt_pk_bf16_f32 v62, v88, v89
	v_cvt_pk_bf16_f32 v63, v90, v91
	v_cvt_pk_bf16_f32 v64, v92, v93
	v_cvt_pk_bf16_f32 v65, v94, v95
	v_cvt_pk_bf16_f32 v66, v96, v97
	v_cvt_pk_bf16_f32 v67, v98, v99
	ds_write_b128 v142, v[60:63] offset:9216
	ds_write_b128 v142, v[64:67] offset:18432
	ds_write_b128 v142, v[12:15] offset:36864
	v_lshl_add_u64 v[224:225], v[224:225], 0, s[30:31]
	global_load_dwordx4 v[12:15], v[224:225], off
	s_branch .LBB0_877
.Lf1_prep_slow:
	v_cvt_f32_f16 v28, v24
	v_lshrrev_b32_e32 v0, 16, v24
	v_cvt_f32_f16 v29, v0
	v_cvt_f32_f16 v30, v25
	v_lshrrev_b32_e32 v0, 16, v25
	v_cvt_f32_f16 v31, v0
	v_cvt_f32_f16 v32, v26
	v_lshrrev_b32_e32 v0, 16, v26
	v_cvt_f32_f16 v33, v0
	v_cvt_f32_f16 v34, v27
	v_lshrrev_b32_e32 v0, 16, v27
	v_cvt_f32_f16 v35, v0
	v_mul_f32_e32 v28, 0x3fb8aa3b, v28
	v_mul_f32_e32 v29, 0x3fb8aa3b, v29
	v_mul_f32_e32 v30, 0x3fb8aa3b, v30
	v_mul_f32_e32 v31, 0x3fb8aa3b, v31
	v_mul_f32_e32 v32, 0x3fb8aa3b, v32
	v_mul_f32_e32 v33, 0x3fb8aa3b, v33
	v_mul_f32_e32 v34, 0x3fb8aa3b, v34
	v_mul_f32_e32 v35, 0x3fb8aa3b, v35
	v_add_f32_dpp v28, v28, v28 row_shr:1 row_mask:0xf bank_mask:0xf bound_ctrl:1
	v_add_f32_dpp v29, v29, v29 row_shr:1 row_mask:0xf bank_mask:0xf bound_ctrl:1
	v_add_f32_dpp v30, v30, v30 row_shr:1 row_mask:0xf bank_mask:0xf bound_ctrl:1
	v_add_f32_dpp v31, v31, v31 row_shr:1 row_mask:0xf bank_mask:0xf bound_ctrl:1
	v_add_f32_dpp v32, v32, v32 row_shr:1 row_mask:0xf bank_mask:0xf bound_ctrl:1
	v_add_f32_dpp v33, v33, v33 row_shr:1 row_mask:0xf bank_mask:0xf bound_ctrl:1
	v_add_f32_dpp v34, v34, v34 row_shr:1 row_mask:0xf bank_mask:0xf bound_ctrl:1
	v_add_f32_dpp v35, v35, v35 row_shr:1 row_mask:0xf bank_mask:0xf bound_ctrl:1
	v_add_f32_dpp v28, v28, v28 row_shr:2 row_mask:0xf bank_mask:0xf bound_ctrl:1
	v_add_f32_dpp v29, v29, v29 row_shr:2 row_mask:0xf bank_mask:0xf bound_ctrl:1
	v_add_f32_dpp v30, v30, v30 row_shr:2 row_mask:0xf bank_mask:0xf bound_ctrl:1
	v_add_f32_dpp v31, v31, v31 row_shr:2 row_mask:0xf bank_mask:0xf bound_ctrl:1
	v_add_f32_dpp v32, v32, v32 row_shr:2 row_mask:0xf bank_mask:0xf bound_ctrl:1
	v_add_f32_dpp v33, v33, v33 row_shr:2 row_mask:0xf bank_mask:0xf bound_ctrl:1
	v_add_f32_dpp v34, v34, v34 row_shr:2 row_mask:0xf bank_mask:0xf bound_ctrl:1
	v_add_f32_dpp v35, v35, v35 row_shr:2 row_mask:0xf bank_mask:0xf bound_ctrl:1
	v_add_f32_dpp v28, v28, v28 row_shr:4 row_mask:0xf bank_mask:0xf bound_ctrl:1
	v_add_f32_dpp v29, v29, v29 row_shr:4 row_mask:0xf bank_mask:0xf bound_ctrl:1
	v_add_f32_dpp v30, v30, v30 row_shr:4 row_mask:0xf bank_mask:0xf bound_ctrl:1
	v_add_f32_dpp v31, v31, v31 row_shr:4 row_mask:0xf bank_mask:0xf bound_ctrl:1
	v_add_f32_dpp v32, v32, v32 row_shr:4 row_mask:0xf bank_mask:0xf bound_ctrl:1
	v_add_f32_dpp v33, v33, v33 row_shr:4 row_mask:0xf bank_mask:0xf bound_ctrl:1
	v_add_f32_dpp v34, v34, v34 row_shr:4 row_mask:0xf bank_mask:0xf bound_ctrl:1
	v_add_f32_dpp v35, v35, v35 row_shr:4 row_mask:0xf bank_mask:0xf bound_ctrl:1
	v_add_f32_dpp v28, v28, v28 row_shr:8 row_mask:0xf bank_mask:0xf bound_ctrl:1
	v_add_f32_dpp v29, v29, v29 row_shr:8 row_mask:0xf bank_mask:0xf bound_ctrl:1
	v_add_f32_dpp v30, v30, v30 row_shr:8 row_mask:0xf bank_mask:0xf bound_ctrl:1
	v_add_f32_dpp v31, v31, v31 row_shr:8 row_mask:0xf bank_mask:0xf bound_ctrl:1
	v_add_f32_dpp v32, v32, v32 row_shr:8 row_mask:0xf bank_mask:0xf bound_ctrl:1
	v_add_f32_dpp v33, v33, v33 row_shr:8 row_mask:0xf bank_mask:0xf bound_ctrl:1
	v_add_f32_dpp v34, v34, v34 row_shr:8 row_mask:0xf bank_mask:0xf bound_ctrl:1
	v_add_f32_dpp v35, v35, v35 row_shr:8 row_mask:0xf bank_mask:0xf bound_ctrl:1
	v_add_f32_dpp v28, v28, v28 row_bcast:15 row_mask:0xa bank_mask:0xf
	v_add_f32_dpp v29, v29, v29 row_bcast:15 row_mask:0xa bank_mask:0xf
	v_add_f32_dpp v30, v30, v30 row_bcast:15 row_mask:0xa bank_mask:0xf
	v_add_f32_dpp v31, v31, v31 row_bcast:15 row_mask:0xa bank_mask:0xf
	v_add_f32_dpp v32, v32, v32 row_bcast:15 row_mask:0xa bank_mask:0xf
	v_add_f32_dpp v33, v33, v33 row_bcast:15 row_mask:0xa bank_mask:0xf
	v_add_f32_dpp v34, v34, v34 row_bcast:15 row_mask:0xa bank_mask:0xf
	v_add_f32_dpp v35, v35, v35 row_bcast:15 row_mask:0xa bank_mask:0xf
	v_add_f32_dpp v28, v28, v28 row_bcast:31 row_mask:0xc bank_mask:0xf
	v_add_f32_dpp v29, v29, v29 row_bcast:31 row_mask:0xc bank_mask:0xf
	v_add_f32_dpp v30, v30, v30 row_bcast:31 row_mask:0xc bank_mask:0xf
	v_add_f32_dpp v31, v31, v31 row_bcast:31 row_mask:0xc bank_mask:0xf
	v_add_f32_dpp v32, v32, v32 row_bcast:31 row_mask:0xc bank_mask:0xf
	v_add_f32_dpp v33, v33, v33 row_bcast:31 row_mask:0xc bank_mask:0xf
	v_add_f32_dpp v34, v34, v34 row_bcast:31 row_mask:0xc bank_mask:0xf
	v_add_f32_dpp v35, v35, v35 row_bcast:31 row_mask:0xc bank_mask:0xf
	v_exp_f32_e32 v36, v28
	v_lshlrev_b32_e32 v68, 16, v16
	v_and_b32_e32 v69, 0xffff0000, v16
	v_exp_f32_e32 v37, v29
	v_lshlrev_b32_e32 v70, 16, v17
	v_and_b32_e32 v71, 0xffff0000, v17
	v_exp_f32_e32 v38, v30
	v_lshlrev_b32_e32 v72, 16, v18
	v_and_b32_e32 v73, 0xffff0000, v18
	v_exp_f32_e32 v39, v31
	v_lshlrev_b32_e32 v74, 16, v19
	v_and_b32_e32 v75, 0xffff0000, v19
	v_exp_f32_e32 v40, v32
	v_lshlrev_b32_e32 v76, 16, v4
	v_and_b32_e32 v77, 0xffff0000, v4
	v_exp_f32_e32 v41, v33
	v_lshlrev_b32_e32 v78, 16, v5
	v_and_b32_e32 v79, 0xffff0000, v5
	v_exp_f32_e32 v42, v34
	v_lshlrev_b32_e32 v80, 16, v6
	v_and_b32_e32 v81, 0xffff0000, v6
	v_exp_f32_e32 v43, v35
	v_lshlrev_b32_e32 v82, 16, v7
	v_and_b32_e32 v83, 0xffff0000, v7
	v_exp_f32_e64 v44, -v28
	v_lshlrev_b32_e32 v84, 16, v20
	v_and_b32_e32 v85, 0xffff0000, v20
	v_exp_f32_e64 v45, -v29
	v_lshlrev_b32_e32 v86, 16, v21
	v_and_b32_e32 v87, 0xffff0000, v21
	v_exp_f32_e64 v46, -v30
	v_lshlrev_b32_e32 v88, 16, v22
	v_and_b32_e32 v89, 0xffff0000, v22
	v_exp_f32_e64 v47, -v31
	v_lshlrev_b32_e32 v90, 16, v23
	v_and_b32_e32 v91, 0xffff0000, v23
	v_exp_f32_e64 v48, -v32
	v_lshlrev_b32_e32 v92, 16, v8
	v_and_b32_e32 v93, 0xffff0000, v8
	v_exp_f32_e64 v49, -v33
	v_lshlrev_b32_e32 v94, 16, v9
	v_and_b32_e32 v95, 0xffff0000, v9
	v_exp_f32_e64 v50, -v34
	v_lshlrev_b32_e32 v96, 16, v10
	v_and_b32_e32 v97, 0xffff0000, v10
	v_exp_f32_e64 v51, -v35
	v_lshlrev_b32_e32 v98, 16, v11
	v_and_b32_e32 v99, 0xffff0000, v11
	v_mov_b32_dpp v212, v36 wave_shr:1 row_mask:0xf bank_mask:0xf
	v_mov_b32_dpp v213, v37 wave_shr:1 row_mask:0xf bank_mask:0xf
	v_mov_b32_dpp v214, v38 wave_shr:1 row_mask:0xf bank_mask:0xf
	v_mov_b32_dpp v215, v39 wave_shr:1 row_mask:0xf bank_mask:0xf
	v_mov_b32_dpp v216, v40 wave_shr:1 row_mask:0xf bank_mask:0xf
	v_mov_b32_dpp v217, v41 wave_shr:1 row_mask:0xf bank_mask:0xf
	v_mov_b32_dpp v218, v42 wave_shr:1 row_mask:0xf bank_mask:0xf
	v_mov_b32_dpp v219, v43 wave_shr:1 row_mask:0xf bank_mask:0xf
	v_readlane_b32 s9, v254, 60
	s_add_i32 s9, s9, 0x21c00
	v_mov_b32_e32 v0, s9
	s_mov_b64 s[84:85], exec
	s_andn2_b64 exec, exec, s[38:39]
	ds_write_b128 v0, v[36:39]
	ds_write_b128 v0, v[40:43] offset:16
	s_mov_b64 exec, s[84:85]
	v_pk_mul_f32 v[68:69], v[212:213], v[68:69] neg_lo:[0,1] neg_hi:[0,1]
	v_pk_mul_f32 v[70:71], v[214:215], v[70:71] neg_lo:[0,1] neg_hi:[0,1]
	v_pk_mul_f32 v[72:73], v[216:217], v[72:73] neg_lo:[0,1] neg_hi:[0,1]
	v_pk_mul_f32 v[74:75], v[218:219], v[74:75] neg_lo:[0,1] neg_hi:[0,1]
	v_pk_mul_f32 v[76:77], v[36:37], v[76:77]
	v_pk_mul_f32 v[78:79], v[38:39], v[78:79]
	v_pk_mul_f32 v[80:81], v[40:41], v[80:81]
	v_pk_mul_f32 v[82:83], v[42:43], v[82:83]
	v_pk_mul_f32 v[84:85], v[44:45], v[84:85]
	v_pk_mul_f32 v[86:87], v[46:47], v[86:87]
	v_pk_mul_f32 v[88:89], v[48:49], v[88:89]
	v_pk_mul_f32 v[90:91], v[50:51], v[90:91]
	v_pk_mul_f32 v[92:93], v[44:45], v[92:93]
	v_pk_mul_f32 v[94:95], v[46:47], v[94:95]
	v_pk_mul_f32 v[96:97], v[48:49], v[96:97]
	v_pk_mul_f32 v[98:99], v[50:51], v[98:99]
	v_cvt_pk_bf16_f32 v52, v68, v69
	v_cvt_pk_bf16_f32 v53, v70, v71
	v_cvt_pk_bf16_f32 v54, v72, v73
	v_cvt_pk_bf16_f32 v55, v74, v75
	v_cvt_pk_bf16_f32 v56, v76, v77
	v_cvt_pk_bf16_f32 v57, v78, v79
	v_cvt_pk_bf16_f32 v58, v80, v81
	v_cvt_pk_bf16_f32 v59, v82, v83
	ds_write_b128 v142, v[52:55]
	ds_write_b128 v142, v[56:59] offset:27648
	v_cvt_pk_bf16_f32 v60, v84, v85
	v_cvt_pk_bf16_f32 v61, v86, v87
	v_cvt_pk_bf16_f32 v62, v88, v89
	v_cvt_pk_bf16_f32 v63, v90, v91
	v_cvt_pk_bf16_f32 v64, v92, v93
	v_cvt_pk_bf16_f32 v65, v94, v95
	v_cvt_pk_bf16_f32 v66, v96, v97
	v_cvt_pk_bf16_f32 v67, v98, v99
	ds_write_b128 v142, v[60:63] offset:9216
	ds_write_b128 v142, v[64:67] offset:18432
	ds_write_b128 v142, v[12:15] offset:36864
	s_and_b64 vcc, exec, s[22:23]
	s_cbranch_vccnz .LBB0_877
	s_mul_hi_i32 s8, s91, 0x3e0f83e1
	s_mov_b64 s[94:95], s[20:21]
	s_mov_b64 s[20:21], s[68:69]
	s_mov_b64 s[68:69], s[66:67]
	s_mov_b64 s[66:67], s[64:65]
	s_mov_b64 s[64:65], s[62:63]
	s_mov_b64 s[62:63], s[18:19]
	s_mov_b64 s[18:19], s[46:47]
	s_mov_b64 s[46:47], s[44:45]
	s_mov_b64 s[44:45], s[42:43]
	s_mov_b64 s[42:43], s[40:41]
	s_mov_b64 s[40:41], s[38:39]
	s_lshr_b32 s9, s8, 31
	s_ashr_i32 s39, s8, 5
	s_add_i32 s39, s39, s9
	s_mul_i32 s8, s39, 0xffffff7c
	s_add_i32 vcc_lo, s90, s8
	s_add_i32 s34, vcc_lo, 1
	s_ashr_i32 s35, s39, 5
	s_and_b32 s38, s39, 1
	s_cmp_eq_u32 s38, 0
	s_cselect_b64 s[84:85], -1, 0
	s_cmp_gt_i32 s34, 3
	s_mov_b64 s[86:87], -1
	s_mul_i32 s8, s39, 0x84
	s_cbranch_scc0 .LBB0_874
	s_add_i32 s9, s27, s8
	s_add_i32 vcc_lo, vcc_lo, -3
	s_and_b64 s[86:87], s[84:85], exec
	s_cselect_b32 s9, vcc_lo, s9
	s_lshl_b32 s86, s35, 13
	s_lshl_b32 s9, s9, 6
	s_add_i32 s9, s9, s86
	s_mov_b64 s[86:87], 0

.LBB0_876:
	v_cndmask_b32_e64 v0, v115, v114, s[84:85]
	s_lshl_b32 s8, s39, 5
	v_add_u32_e32 v0, s9, v0
	s_and_b32 s8, s8, 0x3c0
	v_readlane_b32 s9, v254, 46
	v_ashrrev_i32_e32 v1, 31, v0
	s_add_u32 s8, s8, s9
	v_readlane_b32 s9, v254, 47
	v_lshlrev_b64 v[0:1], 10, v[0:1]
	s_addc_u32 s9, 0, s9
	v_lshl_add_u64 v[0:1], s[8:9], 0, v[0:1]
	v_readlane_b32 s8, v254, 48
	v_lshlrev_b64 v[0:1], 1, v[0:1]
	v_readlane_b32 s9, v254, 49
	s_mul_i32 s38, s38, 0x2100000
	s_nop 0
	v_lshl_add_u64 v[4:5], s[8:9], 0, v[0:1]
	v_readlane_b32 s8, v254, 50
	s_add_u32 s8, s8, s38
	v_readlane_b32 s9, v254, 51
	s_addc_u32 s9, s9, 0
	s_nop 0
	v_lshl_add_u64 v[8:9], s[8:9], 0, v[0:1]
	v_readlane_b32 s8, v254, 52
	v_readlane_b32 s9, v254, 53
	v_mov_b32_e32 v220, v4
	v_mov_b32_e32 v221, v5
	global_load_dwordx4 v[4:7], v[4:5], off
	s_nop 0
	v_mov_b32_e32 v222, v8
	v_mov_b32_e32 v223, v9
	global_load_dwordx4 v[8:11], v[8:9], off
	v_lshl_add_u64 v[12:13], s[8:9], 0, v[0:1]
	v_readlane_b32 s8, v254, 54
	v_readlane_b32 s9, v254, 55
	s_nop 1
	v_lshl_add_u64 v[16:17], s[8:9], 0, v[0:1]
	v_readlane_b32 s8, v254, 56
	s_add_u32 s8, s8, s38
	v_readlane_b32 s9, v254, 57
	s_addc_u32 s9, s9, 0
	v_mov_b32_e32 v224, v12
	v_mov_b32_e32 v225, v13
	global_load_dwordx4 v[12:15], v[12:13], off
	s_nop 0
	v_mov_b32_e32 v226, v16
	v_mov_b32_e32 v227, v17
	global_load_dwordx4 v[16:19], v[16:17], off
	v_lshl_add_u64 v[20:21], s[8:9], 0, v[0:1]
	v_readlane_b32 s8, v254, 58
	s_add_u32 s8, s8, s38
	v_readlane_b32 s9, v254, 59
	s_addc_u32 s9, s9, 0
	s_mov_b64 s[38:39], s[40:41]
	v_lshl_add_u64 v[0:1], s[8:9], 0, v[0:1]
	v_mov_b32_e32 v228, v20
	v_mov_b32_e32 v229, v21
	global_load_dwordx4 v[20:23], v[20:21], off
	s_nop 0
	v_mov_b32_e32 v230, v0
	v_mov_b32_e32 v231, v1
	global_load_dwordx4 v[24:27], v[0:1], off
	s_mov_b64 s[40:41], s[42:43]
	s_mov_b64 s[42:43], s[44:45]
	s_mov_b64 s[44:45], s[46:47]
	s_mov_b64 s[46:47], s[18:19]
	s_mov_b64 s[18:19], s[62:63]
	s_mov_b64 s[62:63], s[64:65]
	s_mov_b64 s[64:65], s[66:67]
	s_mov_b64 s[66:67], s[68:69]
	s_mov_b64 s[68:69], s[20:21]
	s_mov_b64 s[20:21], s[94:95]
	s_mov_b64 s[94:95], 0x400800

	.amdhsa_kernel _Z8skel_fwd4Args
		.amdhsa_group_segment_fixed_size 0
		.amdhsa_private_segment_fixed_size 0
		.amdhsa_kernarg_size 488
		.amdhsa_user_sgpr_count 2
		.amdhsa_user_sgpr_dispatch_ptr 0
		.amdhsa_user_sgpr_queue_ptr 0
		.amdhsa_user_sgpr_kernarg_segment_ptr 1
		.amdhsa_user_sgpr_dispatch_id 0
		.amdhsa_user_sgpr_kernarg_preload_length 0
		.amdhsa_user_sgpr_kernarg_preload_offset 0
		.amdhsa_user_sgpr_private_segment_size 0
		.amdhsa_uses_dynamic_stack 0
		.amdhsa_enable_private_segment 0
		.amdhsa_system_sgpr_workgroup_id_x 1
		.amdhsa_system_sgpr_workgroup_id_y 0
		.amdhsa_system_sgpr_workgroup_id_z 0
		.amdhsa_system_sgpr_workgroup_info 0
		.amdhsa_system_vgpr_workitem_id 0
		.amdhsa_next_free_vgpr 256
		.amdhsa_next_free_sgpr 102
		.amdhsa_accum_offset 256
		.amdhsa_reserve_vcc 1
		.amdhsa_float_round_mode_32 0
		.amdhsa_float_round_mode_16_64 0
		.amdhsa_float_denorm_mode_32 3
		.amdhsa_float_denorm_mode_16_64 3
		.amdhsa_dx10_clamp 1
		.amdhsa_ieee_mode 1
		.amdhsa_fp16_overflow 0
		.amdhsa_tg_split 0
		.amdhsa_exception_fp_ieee_invalid_op 0
		.amdhsa_exception_fp_denorm_src 0
		.amdhsa_exception_fp_ieee_div_zero 0
		.amdhsa_exception_fp_ieee_overflow 0
		.amdhsa_exception_fp_ieee_underflow 0
		.amdhsa_exception_fp_ieee_inexact 0
		.amdhsa_exception_int_div_zero 0
	.end_amdhsa_kernel

amdhsa.kernels:
  - .agpr_count:     0
    .args:
      - .offset:         0
        .size:           232
        .value_kind:     by_value
      - .offset:         232
        .size:           4
        .value_kind:     hidden_block_count_x
      - .offset:         236
        .size:           4
        .value_kind:     hidden_block_count_y
      - .offset:         240
        .size:           4
        .value_kind:     hidden_block_count_z
      - .offset:         244
        .size:           2
        .value_kind:     hidden_group_size_x
      - .offset:         246
        .size:           2
        .value_kind:     hidden_group_size_y
      - .offset:         248
        .size:           2
        .value_kind:     hidden_group_size_z
      - .offset:         250
        .size:           2
        .value_kind:     hidden_remainder_x
      - .offset:         252
        .size:           2
        .value_kind:     hidden_remainder_y
      - .offset:         254
        .size:           2
        .value_kind:     hidden_remainder_z
      - .offset:         272
        .size:           8
        .value_kind:     hidden_global_offset_x
      - .offset:         280
        .size:           8
        .value_kind:     hidden_global_offset_y
      - .offset:         288
        .size:           8
        .value_kind:     hidden_global_offset_z
      - .offset:         296
        .size:           2
        .value_kind:     hidden_grid_dims
      - .offset:         352
        .size:           4
        .value_kind:     hidden_dynamic_lds_size
    .group_segment_fixed_size: 0
    .kernarg_segment_align: 8
    .kernarg_segment_size: 488
    .language:       OpenCL C
    .language_version:
      - 2
      - 0
    .max_flat_workgroup_size: 512
    .name:           _Z8skel_fwd4Args
    .private_segment_fixed_size: 0
    .sgpr_count:     108
    .sgpr_spill_count: 134
    .symbol:         _Z8skel_fwd4Args.kd
    .uniform_work_group_size: 1
    .uses_dynamic_stack: false
    .vgpr_count:     256
    .vgpr_spill_count: 0
    .wavefront_size: 64
